# v20: SB diagonal tile computed with the straight-line tile math + 32 v_cndmask instead of 16 exec-masked branches (bit-identical)
# speedup vs baseline: 1.0048x; 1.0046x over previous
; #define MFMA32(a, b, c) __builtin_amdgcn_mfma_f32_32x32x16_bf16((a), (b), (c), 0, 0, 0)
; template <int MODE>
; DI bool attn_tile(const bf16x8 (&kf)[4], const bf16x8 (&vf)[4], const bf16x8 (&qf)[4], int key0, int q0, int tq, int hi, int x32, int own, unsigned selmask,
;                   float& m_run, float& l_run, f32x16& O0, f32x16& O1) {
;     f32x16 s = zero16();
; #pragma unroll
;     for (int kk = 0; kk < 4; ++kk) s = MFMA32(kf[kk], qf[kk], s);
;     if constexpr (MODE == 0) {
;         float lk[16];
;         if (key0 == q0) {
; #pragma unroll
;             for (int i = 0; i < 16; ++i) {
;                 const int key = key0 + 16 * (i >> 3) + 8 * hi + (i & 7);
;                 const bool past = key < tq;
;                 const float z = s[i] * SC2;
;                 const float l1 = __builtin_amdgcn_logf(1.f + __builtin_amdgcn_exp2f(-fabsf(z)));
;                 s[i] = past ? (fminf(z, 0.f) - l1) : -INFINITY;
;                 lk[i] = past ? -(fmaxf(z, 0.f) + l1) : 0.f;
;             }
;         } else {
; #pragma unroll
;             for (int i = 0; i < 16; ++i) {
;                 const float z = s[i] * SC2;
;                 const float l1 = __builtin_amdgcn_logf(1.f + __builtin_amdgcn_exp2f(-fabsf(z)));
;                 s[i] = fminf(z, 0.f) - l1; lk[i] = -(fmaxf(z, 0.f) + l1);
;             }
.LBB0_533:
	s_waitcnt vmcnt(0) lgkmcnt(0)
	v_mfma_f32_32x32x16_bf16 v[34:49], v[34:37], v[82:85], 0
	s_mov_b64 s[46:47], -1
	v_mfma_f32_32x32x16_bf16 v[34:49], v[54:57], v[86:89], v[34:49]
	v_mfma_f32_32x32x16_bf16 v[34:49], v[50:53], v[90:93], v[34:49]
	v_sub_co_u32_e64 v50, s[80:81], s96, 1
	s_nop 0
	v_readfirstlane_b32 s96, v50
	s_and_b64 vcc, exec, s[80:81]
	v_mfma_f32_32x32x16_bf16 v[34:49], v[58:61], v[94:97], v[34:49]
	s_nop 11
	v_mul_f32_e32 v66, 0x3e38aa3b, v39
	v_mul_f32_e32 v67, 0x3e38aa3b, v40
	v_exp_f32_e64 v65, -|v66|
	v_exp_f32_e64 v68, -|v67|
	v_mul_f32_e32 v63, 0x3e38aa3b, v38
	v_exp_f32_e64 v62, -|v63|
	v_min_f32_e32 v64, 0, v63
	v_max_f32_e32 v124, 0, v63
	v_add_f32_e32 v63, 1.0, v65
	v_min_f32_e32 v65, 0, v66
	v_max_f32_e32 v125, 0, v66
	v_add_f32_e32 v66, 1.0, v68
	v_mul_f32_e32 v68, 0x3e38aa3b, v41
	v_exp_f32_e64 v69, -|v68|
	v_min_f32_e32 v72, 0, v67
	v_max_f32_e32 v128, 0, v67
	v_mul_f32_e32 v67, 0x3e38aa3b, v42
	v_log_f32_e32 v126, v66
	v_add_f32_e32 v66, 1.0, v69
	v_exp_f32_e64 v69, -|v67|
	v_min_f32_e32 v73, 0, v68
	v_max_f32_e32 v129, 0, v68
	v_mul_f32_e32 v68, 0x3e38aa3b, v43
	v_log_f32_e32 v127, v66
	v_add_f32_e32 v66, 1.0, v69
	v_exp_f32_e64 v69, -|v68|
	v_min_f32_e32 v74, 0, v67
	v_max_f32_e32 v132, 0, v67
	v_mul_f32_e32 v67, 0x3e38aa3b, v44
	v_log_f32_e32 v130, v66
	v_add_f32_e32 v66, 1.0, v69
	v_exp_f32_e64 v69, -|v67|
	v_min_f32_e32 v75, 0, v68
	v_max_f32_e32 v133, 0, v68
	v_mul_f32_e32 v68, 0x3e38aa3b, v45
	v_log_f32_e32 v131, v66
	v_add_f32_e32 v66, 1.0, v69
	v_exp_f32_e64 v69, -|v68|
	v_min_f32_e32 v76, 0, v67
	v_max_f32_e32 v136, 0, v67
	v_mul_f32_e32 v67, 0x3e38aa3b, v46
	v_log_f32_e32 v134, v66
	v_add_f32_e32 v66, 1.0, v69
	v_exp_f32_e64 v69, -|v67|
	v_min_f32_e32 v77, 0, v68
	v_max_f32_e32 v137, 0, v68
	v_mul_f32_e32 v68, 0x3e38aa3b, v47
	v_log_f32_e32 v135, v66
	v_add_f32_e32 v66, 1.0, v69
	v_exp_f32_e64 v69, -|v68|
	v_min_f32_e32 v78, 0, v67
	v_max_f32_e32 v140, 0, v67
	v_mul_f32_e32 v67, 0x3e38aa3b, v48
	v_mul_f32_e32 v51, 0x3e38aa3b, v34
	v_mul_f32_e32 v55, 0x3e38aa3b, v35
	v_mul_f32_e32 v57, 0x3e38aa3b, v36
	v_mul_f32_e32 v61, 0x3e38aa3b, v37
	v_log_f32_e32 v138, v66
	v_add_f32_e32 v66, 1.0, v69
	v_exp_f32_e64 v69, -|v67|
	v_mul_f32_e32 v145, 0x3e38aa3b, v49
	v_exp_f32_e64 v52, -|v51|
	v_exp_f32_e64 v53, -|v55|
	v_exp_f32_e64 v56, -|v57|
	v_exp_f32_e64 v59, -|v61|
	v_min_f32_e32 v79, 0, v68
	v_max_f32_e32 v141, 0, v68
	v_exp_f32_e64 v68, -|v145|
	v_log_f32_e32 v139, v66
	v_add_f32_e32 v66, 1.0, v69
	v_min_f32_e32 v50, 0, v51
	v_add_f32_e32 v52, 1.0, v52
	v_max_f32_e32 v54, 0, v51
	v_add_f32_e32 v51, 1.0, v53
	v_add_f32_e32 v56, 1.0, v56
	v_min_f32_e32 v58, 0, v57
	v_max_f32_e32 v60, 0, v57
	v_add_f32_e32 v57, 1.0, v59
	v_add_f32_e32 v62, 1.0, v62
	v_log_f32_e32 v142, v66
	v_add_f32_e32 v66, 1.0, v68
	v_log_f32_e32 v52, v52
	v_log_f32_e32 v53, v51
	v_log_f32_e32 v56, v56
	v_log_f32_e32 v57, v57
	v_log_f32_e32 v62, v62
	v_log_f32_e32 v63, v63
	v_log_f32_e32 v143, v66
	v_min_f32_e32 v51, 0, v55
	v_max_f32_e32 v55, 0, v55
	v_min_f32_e32 v59, 0, v61
	v_max_f32_e32 v61, 0, v61
	v_max_f32_e32 v144, 0, v67
	v_min_f32_e32 v81, 0, v145
	v_max_f32_e32 v145, 0, v145
	v_min_f32_e32 v80, 0, v67
	v_pk_add_f32 v[66:67], v[50:51], v[52:53] neg_lo:[0,1] neg_hi:[0,1]
	v_pk_add_f32 v[68:69], v[58:59], v[56:57] neg_lo:[0,1] neg_hi:[0,1]
	v_pk_add_f32 v[70:71], v[64:65], v[62:63] neg_lo:[0,1] neg_hi:[0,1]
	v_pk_add_f32 v[50:51], v[54:55], v[52:53] neg_lo:[1,1] neg_hi:[1,1]
	v_pk_add_f32 v[52:53], v[60:61], v[56:57] neg_lo:[1,1] neg_hi:[1,1]
	v_pk_add_f32 v[54:55], v[124:125], v[62:63] neg_lo:[1,1] neg_hi:[1,1]
	v_pk_add_f32 v[56:57], v[128:129], v[126:127] neg_lo:[1,1] neg_hi:[1,1]
	v_pk_add_f32 v[58:59], v[132:133], v[130:131] neg_lo:[1,1] neg_hi:[1,1]
	v_pk_add_f32 v[60:61], v[136:137], v[134:135] neg_lo:[1,1] neg_hi:[1,1]
	v_pk_add_f32 v[62:63], v[140:141], v[138:139] neg_lo:[1,1] neg_hi:[1,1]
	v_pk_add_f32 v[64:65], v[144:145], v[142:143] neg_lo:[1,1] neg_hi:[1,1]
	v_pk_add_f32 v[72:73], v[72:73], v[126:127] neg_lo:[0,1] neg_hi:[0,1]
	v_pk_add_f32 v[74:75], v[74:75], v[130:131] neg_lo:[0,1] neg_hi:[0,1]
	v_pk_add_f32 v[76:77], v[76:77], v[134:135] neg_lo:[0,1] neg_hi:[0,1]
	v_pk_add_f32 v[78:79], v[78:79], v[138:139] neg_lo:[0,1] neg_hi:[0,1]
	v_pk_add_f32 v[80:81], v[80:81], v[142:143] neg_lo:[0,1] neg_hi:[0,1]
	s_mov_b64 s[46:47], 0
.LBB0_535:
	s_and_b64 vcc, exec, s[80:81]
	s_cbranch_vccz .LBB0_528
	v_cndmask_b32_e64 v66, v66, v208, s[4:5]
	v_cndmask_b32_e64 v50, v50, 0, s[4:5]
	v_cndmask_b32_e64 v67, v67, v208, s[6:7]
	v_cndmask_b32_e64 v51, v51, 0, s[6:7]
	v_cndmask_b32_e64 v68, v68, v208, s[8:9]
	v_cndmask_b32_e64 v52, v52, 0, s[8:9]
	v_cndmask_b32_e64 v69, v69, v208, s[10:11]
	v_cndmask_b32_e64 v53, v53, 0, s[10:11]
	v_cndmask_b32_e64 v70, v70, v208, s[12:13]
	v_cndmask_b32_e64 v54, v54, 0, s[12:13]
	v_cndmask_b32_e64 v71, v71, v208, s[14:15]
	v_cndmask_b32_e64 v55, v55, 0, s[14:15]
	v_cndmask_b32_e64 v72, v72, v208, s[16:17]
	v_cndmask_b32_e64 v56, v56, 0, s[16:17]
	v_cndmask_b32_e64 v73, v73, v208, s[18:19]
	v_cndmask_b32_e64 v57, v57, 0, s[18:19]
	v_cndmask_b32_e64 v74, v74, v208, s[20:21]
	v_cndmask_b32_e64 v58, v58, 0, s[20:21]
	v_cndmask_b32_e64 v75, v75, v208, s[22:23]
	v_cndmask_b32_e64 v59, v59, 0, s[22:23]
	v_cndmask_b32_e64 v76, v76, v208, s[24:25]
	v_cndmask_b32_e64 v60, v60, 0, s[24:25]
	v_cndmask_b32_e64 v77, v77, v208, s[26:27]
	v_cndmask_b32_e64 v61, v61, 0, s[26:27]
	v_cndmask_b32_e64 v78, v78, v208, s[28:29]
	v_cndmask_b32_e64 v62, v62, 0, s[28:29]
	v_cndmask_b32_e64 v79, v79, v208, s[30:31]
	v_cndmask_b32_e64 v63, v63, 0, s[30:31]
	v_cndmask_b32_e64 v80, v80, v208, s[34:35]
	v_cndmask_b32_e64 v64, v64, 0, s[34:35]
	v_cndmask_b32_e64 v81, v81, v208, s[36:37]
	v_cndmask_b32_e64 v65, v65, 0, s[36:37]
	s_branch .LBB0_528
